# c18 plus forget-gate logit GEMV operands staged through LDS with 1-KiB-contiguous LDS-DMA loads and ds_read_b128 fragments instead of 16-row x 64-B direct loads
# speedup vs baseline: 1.0031x; 1.0031x over previous
.LBB0_997:
	s_add_i32 s6, s6, s10
	v_add_u32_e32 v0, s6, v25
	v_ashrrev_i32_e32 v1, 31, v0
	v_lshlrev_b64 v[0:1], 12, v[0:1]
	v_lshl_add_u64 v[22:23], v[8:9], 0, v[0:1]
	v_readlane_b32 s35, v254, 24
	v_mbcnt_lo_u32_b32 v90, -1, 0
	v_mbcnt_hi_u32_b32 v90, -1, v90
	v_readfirstlane_b32 s36, v22
	v_readfirstlane_b32 s37, v23
	v_readfirstlane_b32 s38, v12
	v_readfirstlane_b32 s39, v13
	s_lshr_b32 s40, s35, 6
	s_lshr_b32 s41, s35, 8
	s_and_b32 s42, s40, 3
	s_lshl_b32 s43, s41, 11
	s_sub_u32 s44, s38, s43
	s_subb_u32 s45, s39, 0
	s_lshl_b32 s49, s40, 13
	s_add_i32 s49, s49, 0x10000
	v_and_b32_e32 v91, 31, v90
	v_lshrrev_b32_e32 v92, 5, v90
	v_and_b32_e32 v93, 15, v90
	v_lshrrev_b32_e32 v94, 4, v90
	s_add_i32 s46, s41, 0
	v_xor_b32_e32 v95, s46, v91
	v_lshlrev_b32_e32 v95, 4, v95
	v_lshl_add_u32 v95, v92, 9, v95
	s_lshl_b32 s47, s46, 12
	s_lshl_b32 s48, s42, 10
	s_add_i32 s47, s47, s48
	v_add_u32_e32 v95, s47, v95
	s_lshl_b32 s48, s40, 10
	s_add_i32 m0, s48, 0x0
	s_nop 0
	global_load_lds_dwordx4 v95, s[44:45]
	s_add_i32 s46, s41, 2
	v_xor_b32_e32 v95, s46, v91
	v_lshlrev_b32_e32 v95, 4, v95
	v_lshl_add_u32 v95, v92, 9, v95
	s_lshl_b32 s47, s46, 12
	s_lshl_b32 s48, s42, 10
	s_add_i32 s47, s47, s48
	v_add_u32_e32 v95, s47, v95
	s_lshl_b32 s48, s40, 10
	s_add_i32 m0, s48, 0x2000
	s_nop 0
	global_load_lds_dwordx4 v95, s[44:45]
	s_add_i32 s46, s41, 4
	v_xor_b32_e32 v95, s46, v91
	v_lshlrev_b32_e32 v95, 4, v95
	v_lshl_add_u32 v95, v92, 9, v95
	s_lshl_b32 s47, s46, 12
	s_lshl_b32 s48, s42, 10
	s_add_i32 s47, s47, s48
	v_add_u32_e32 v95, s47, v95
	s_lshl_b32 s48, s40, 10
	s_add_i32 m0, s48, 0x4000
	s_nop 0
	global_load_lds_dwordx4 v95, s[44:45]
	s_add_i32 s46, s41, 6
	v_xor_b32_e32 v95, s46, v91
	v_lshlrev_b32_e32 v95, 4, v95
	v_lshl_add_u32 v95, v92, 9, v95
	s_lshl_b32 s47, s46, 12
	s_lshl_b32 s48, s42, 10
	s_add_i32 s47, s47, s48
	v_add_u32_e32 v95, s47, v95
	s_lshl_b32 s48, s40, 10
	s_add_i32 m0, s48, 0x6000
	s_nop 0
	global_load_lds_dwordx4 v95, s[44:45]
	s_add_i32 s46, s41, 8
	v_xor_b32_e32 v95, s46, v91
	v_lshlrev_b32_e32 v95, 4, v95
	v_lshl_add_u32 v95, v92, 9, v95
	s_lshl_b32 s47, s46, 12
	s_lshl_b32 s48, s42, 10
	s_add_i32 s47, s47, s48
	v_add_u32_e32 v95, s47, v95
	s_lshl_b32 s48, s40, 10
	s_add_i32 m0, s48, 0x8000
	s_nop 0
	global_load_lds_dwordx4 v95, s[44:45]
	s_add_i32 s46, s41, 10
	v_xor_b32_e32 v95, s46, v91
	v_lshlrev_b32_e32 v95, 4, v95
	v_lshl_add_u32 v95, v92, 9, v95
	s_lshl_b32 s47, s46, 12
	s_lshl_b32 s48, s42, 10
	s_add_i32 s47, s47, s48
	v_add_u32_e32 v95, s47, v95
	s_lshl_b32 s48, s40, 10
	s_add_i32 m0, s48, 0xa000
	s_nop 0
	global_load_lds_dwordx4 v95, s[44:45]
	s_add_i32 s46, s41, 12
	v_xor_b32_e32 v95, s46, v91
	v_lshlrev_b32_e32 v95, 4, v95
	v_lshl_add_u32 v95, v92, 9, v95
	s_lshl_b32 s47, s46, 12
	s_lshl_b32 s48, s42, 10
	s_add_i32 s47, s47, s48
	v_add_u32_e32 v95, s47, v95
	s_lshl_b32 s48, s40, 10
	s_add_i32 m0, s48, 0xc000
	s_nop 0
	global_load_lds_dwordx4 v95, s[44:45]
	s_add_i32 s46, s41, 14
	v_xor_b32_e32 v95, s46, v91
	v_lshlrev_b32_e32 v95, 4, v95
	v_lshl_add_u32 v95, v92, 9, v95
	s_lshl_b32 s47, s46, 12
	s_lshl_b32 s48, s42, 10
	s_add_i32 s47, s47, s48
	v_add_u32_e32 v95, s47, v95
	s_lshl_b32 s48, s40, 10
	s_add_i32 m0, s48, 0xe000
	s_nop 0
	global_load_lds_dwordx4 v95, s[44:45]
	v_add_u32_e32 v96, 0, v94
	v_xor_b32_e32 v96, v96, v93
	v_lshlrev_b32_e32 v96, 4, v96
	v_lshl_add_u32 v100, v93, 9, v96
	v_add_u32_e32 v100, s49, v100
	v_lshl_add_u32 v108, v93, 12, v96
	v_add_u32_e32 v108, s43, v108
	v_add_u32_e32 v96, 4, v94
	v_xor_b32_e32 v96, v96, v93
	v_lshlrev_b32_e32 v96, 4, v96
	v_lshl_add_u32 v101, v93, 9, v96
	v_add_u32_e32 v101, s49, v101
	v_lshl_add_u32 v109, v93, 12, v96
	v_add_u32_e32 v109, s43, v109
	v_add_u32_e32 v96, 8, v94
	v_xor_b32_e32 v96, v96, v93
	v_lshlrev_b32_e32 v96, 4, v96
	v_lshl_add_u32 v102, v93, 9, v96
	v_add_u32_e32 v102, s49, v102
	v_lshl_add_u32 v110, v93, 12, v96
	v_add_u32_e32 v110, s43, v110
	v_add_u32_e32 v96, 12, v94
	v_xor_b32_e32 v96, v96, v93
	v_lshlrev_b32_e32 v96, 4, v96
	v_lshl_add_u32 v103, v93, 9, v96
	v_add_u32_e32 v103, s49, v103
	v_lshl_add_u32 v111, v93, 12, v96
	v_add_u32_e32 v111, s43, v111
	v_add_u32_e32 v96, 16, v94
	v_xor_b32_e32 v96, v96, v93
	v_lshlrev_b32_e32 v96, 4, v96
	v_lshl_add_u32 v104, v93, 9, v96
	v_add_u32_e32 v104, s49, v104
	v_lshl_add_u32 v112, v93, 12, v96
	v_add_u32_e32 v112, s43, v112
	v_add_u32_e32 v96, 20, v94
	v_xor_b32_e32 v96, v96, v93
	v_lshlrev_b32_e32 v96, 4, v96
	v_lshl_add_u32 v105, v93, 9, v96
	v_add_u32_e32 v105, s49, v105
	v_lshl_add_u32 v113, v93, 12, v96
	v_add_u32_e32 v113, s43, v113
	v_add_u32_e32 v96, 24, v94
	v_xor_b32_e32 v96, v96, v93
	v_lshlrev_b32_e32 v96, 4, v96
	v_lshl_add_u32 v106, v93, 9, v96
	v_add_u32_e32 v106, s49, v106
	v_lshl_add_u32 v114, v93, 12, v96
	v_add_u32_e32 v114, s43, v114
	v_add_u32_e32 v96, 28, v94
	v_xor_b32_e32 v96, v96, v93
	v_lshlrev_b32_e32 v96, 4, v96
	v_lshl_add_u32 v107, v93, 9, v96
	v_add_u32_e32 v107, s49, v107
	v_lshl_add_u32 v115, v93, 12, v96
	v_add_u32_e32 v115, s43, v115
	v_add_u32_e32 v96, 0, v92
	v_xor_b32_e32 v97, v96, v91
	v_lshlrev_b32_e32 v97, 4, v97
	v_lshl_add_u32 v116, v96, 12, v97
	v_add_u32_e32 v96, 2, v92
	v_xor_b32_e32 v97, v96, v91
	v_lshlrev_b32_e32 v97, 4, v97
	v_lshl_add_u32 v117, v96, 12, v97
	v_add_u32_e32 v96, 4, v92
	v_xor_b32_e32 v97, v96, v91
	v_lshlrev_b32_e32 v97, 4, v97
	v_lshl_add_u32 v118, v96, 12, v97
	v_add_u32_e32 v96, 6, v92
	v_xor_b32_e32 v97, v96, v91
	v_lshlrev_b32_e32 v97, 4, v97
	v_lshl_add_u32 v119, v96, 12, v97
	v_add_u32_e32 v96, 8, v92
	v_xor_b32_e32 v97, v96, v91
	v_lshlrev_b32_e32 v97, 4, v97
	v_lshl_add_u32 v120, v96, 12, v97
	v_add_u32_e32 v96, 10, v92
	v_xor_b32_e32 v97, v96, v91
	v_lshlrev_b32_e32 v97, 4, v97
	v_lshl_add_u32 v121, v96, 12, v97
	v_add_u32_e32 v96, 12, v92
	v_xor_b32_e32 v97, v96, v91
	v_lshlrev_b32_e32 v97, 4, v97
	v_lshl_add_u32 v122, v96, 12, v97
	v_add_u32_e32 v96, 14, v92
	v_xor_b32_e32 v97, v96, v91
	v_lshlrev_b32_e32 v97, 4, v97
	v_lshl_add_u32 v123, v96, 12, v97
	s_mov_b64 s[50:51], s[36:37]
	s_add_i32 m0, s49, 0x0
	s_nop 0
	global_load_lds_dwordx4 v116, s[50:51]
	s_add_i32 m0, s49, 0x400
	s_nop 0
	global_load_lds_dwordx4 v117, s[50:51]
	s_add_i32 m0, s49, 0x800
	s_nop 0
	global_load_lds_dwordx4 v118, s[50:51]
	s_add_i32 m0, s49, 0xc00
	s_nop 0
	global_load_lds_dwordx4 v119, s[50:51]
	s_add_i32 m0, s49, 0x1000
	s_nop 0
	global_load_lds_dwordx4 v120, s[50:51]
	s_add_i32 m0, s49, 0x1400
	s_nop 0
	global_load_lds_dwordx4 v121, s[50:51]
	s_add_i32 m0, s49, 0x1800
	s_nop 0
	global_load_lds_dwordx4 v122, s[50:51]
	s_add_i32 m0, s49, 0x1c00
	s_nop 0
	global_load_lds_dwordx4 v123, s[50:51]
	s_waitcnt vmcnt(0)
	s_barrier
	ds_read_b128 v[124:127], v100
	ds_read_b128 v[156:159], v108
	ds_read_b128 v[128:131], v101
	ds_read_b128 v[160:163], v109
	ds_read_b128 v[132:135], v102
	ds_read_b128 v[164:167], v110
	ds_read_b128 v[136:139], v103
	ds_read_b128 v[168:171], v111
	ds_read_b128 v[140:143], v104
	ds_read_b128 v[172:175], v112
	ds_read_b128 v[144:147], v105
	ds_read_b128 v[176:179], v113
	ds_read_b128 v[148:151], v106
	ds_read_b128 v[180:183], v114
	ds_read_b128 v[152:155], v107
	ds_read_b128 v[184:187], v115
	s_waitcnt lgkmcnt(0)
	s_add_u32 s50, s36, 0x200
	s_addc_u32 s51, s37, 0
	s_add_i32 m0, s49, 0x0
	s_nop 0
	global_load_lds_dwordx4 v116, s[50:51]
	s_add_i32 m0, s49, 0x400
	s_nop 0
	global_load_lds_dwordx4 v117, s[50:51]
	s_add_i32 m0, s49, 0x800
	s_nop 0
	global_load_lds_dwordx4 v118, s[50:51]
	s_add_i32 m0, s49, 0xc00
	s_nop 0
	global_load_lds_dwordx4 v119, s[50:51]
	s_add_i32 m0, s49, 0x1000
	s_nop 0
	global_load_lds_dwordx4 v120, s[50:51]
	s_add_i32 m0, s49, 0x1400
	s_nop 0
	global_load_lds_dwordx4 v121, s[50:51]
	s_add_i32 m0, s49, 0x1800
	s_nop 0
	global_load_lds_dwordx4 v122, s[50:51]
	s_add_i32 m0, s49, 0x1c00
	s_nop 0
	global_load_lds_dwordx4 v123, s[50:51]
	v_mfma_f32_16x16x32_bf16 v[0:3], v[124:127], v[156:159], 0
	v_mfma_f32_16x16x32_bf16 v[0:3], v[128:131], v[160:163], v[0:3]
	v_mfma_f32_16x16x32_bf16 v[0:3], v[132:135], v[164:167], v[0:3]
	v_mfma_f32_16x16x32_bf16 v[0:3], v[136:139], v[168:171], v[0:3]
	v_mfma_f32_16x16x32_bf16 v[0:3], v[140:143], v[172:175], v[0:3]
	v_mfma_f32_16x16x32_bf16 v[0:3], v[144:147], v[176:179], v[0:3]
	v_mfma_f32_16x16x32_bf16 v[0:3], v[148:151], v[180:183], v[0:3]
	v_mfma_f32_16x16x32_bf16 v[0:3], v[152:155], v[184:187], v[0:3]
	s_waitcnt vmcnt(0)
	ds_read_b128 v[124:127], v100
	ds_read_b128 v[156:159], v108 offset:512
	ds_read_b128 v[128:131], v101
	ds_read_b128 v[160:163], v109 offset:512
	ds_read_b128 v[132:135], v102
	ds_read_b128 v[164:167], v110 offset:512
	ds_read_b128 v[136:139], v103
	ds_read_b128 v[168:171], v111 offset:512
	ds_read_b128 v[140:143], v104
	ds_read_b128 v[172:175], v112 offset:512
	ds_read_b128 v[144:147], v105
	ds_read_b128 v[176:179], v113 offset:512
	ds_read_b128 v[148:151], v106
	ds_read_b128 v[180:183], v114 offset:512
	ds_read_b128 v[152:155], v107
	ds_read_b128 v[184:187], v115 offset:512
	s_waitcnt lgkmcnt(0)
	s_add_u32 s50, s36, 0x400
	s_addc_u32 s51, s37, 0
	s_add_i32 m0, s49, 0x0
	s_nop 0
	global_load_lds_dwordx4 v116, s[50:51]
	s_add_i32 m0, s49, 0x400
	s_nop 0
	global_load_lds_dwordx4 v117, s[50:51]
	s_add_i32 m0, s49, 0x800
	s_nop 0
	global_load_lds_dwordx4 v118, s[50:51]
	s_add_i32 m0, s49, 0xc00
	s_nop 0
	global_load_lds_dwordx4 v119, s[50:51]
	s_add_i32 m0, s49, 0x1000
	s_nop 0
	global_load_lds_dwordx4 v120, s[50:51]
	s_add_i32 m0, s49, 0x1400
	s_nop 0
	global_load_lds_dwordx4 v121, s[50:51]
	s_add_i32 m0, s49, 0x1800
	s_nop 0
	global_load_lds_dwordx4 v122, s[50:51]
	s_add_i32 m0, s49, 0x1c00
	s_nop 0
	global_load_lds_dwordx4 v123, s[50:51]
	v_mfma_f32_16x16x32_bf16 v[0:3], v[124:127], v[156:159], v[0:3]
	v_mfma_f32_16x16x32_bf16 v[0:3], v[128:131], v[160:163], v[0:3]
	v_mfma_f32_16x16x32_bf16 v[0:3], v[132:135], v[164:167], v[0:3]
	v_mfma_f32_16x16x32_bf16 v[0:3], v[136:139], v[168:171], v[0:3]
	v_mfma_f32_16x16x32_bf16 v[0:3], v[140:143], v[172:175], v[0:3]
	v_mfma_f32_16x16x32_bf16 v[0:3], v[144:147], v[176:179], v[0:3]
	v_mfma_f32_16x16x32_bf16 v[0:3], v[148:151], v[180:183], v[0:3]
	v_mfma_f32_16x16x32_bf16 v[0:3], v[152:155], v[184:187], v[0:3]
	s_waitcnt vmcnt(0)
	ds_read_b128 v[124:127], v100
	ds_read_b128 v[156:159], v108 offset:1024
	ds_read_b128 v[128:131], v101
	ds_read_b128 v[160:163], v109 offset:1024
	ds_read_b128 v[132:135], v102
	ds_read_b128 v[164:167], v110 offset:1024
	ds_read_b128 v[136:139], v103
	ds_read_b128 v[168:171], v111 offset:1024
	ds_read_b128 v[140:143], v104
	ds_read_b128 v[172:175], v112 offset:1024
	ds_read_b128 v[144:147], v105
	ds_read_b128 v[176:179], v113 offset:1024
	ds_read_b128 v[148:151], v106
	ds_read_b128 v[180:183], v114 offset:1024
	ds_read_b128 v[152:155], v107
	ds_read_b128 v[184:187], v115 offset:1024
	s_waitcnt lgkmcnt(0)
	s_add_u32 s50, s36, 0x600
	s_addc_u32 s51, s37, 0
	s_add_i32 m0, s49, 0x0
	s_nop 0
	global_load_lds_dwordx4 v116, s[50:51]
	s_add_i32 m0, s49, 0x400
	s_nop 0
	global_load_lds_dwordx4 v117, s[50:51]
	s_add_i32 m0, s49, 0x800
	s_nop 0
	global_load_lds_dwordx4 v118, s[50:51]
	s_add_i32 m0, s49, 0xc00
	s_nop 0
	global_load_lds_dwordx4 v119, s[50:51]
	s_add_i32 m0, s49, 0x1000
	s_nop 0
	global_load_lds_dwordx4 v120, s[50:51]
	s_add_i32 m0, s49, 0x1400
	s_nop 0
	global_load_lds_dwordx4 v121, s[50:51]
	s_add_i32 m0, s49, 0x1800
	s_nop 0
	global_load_lds_dwordx4 v122, s[50:51]
	s_add_i32 m0, s49, 0x1c00
	s_nop 0
	global_load_lds_dwordx4 v123, s[50:51]
	v_mfma_f32_16x16x32_bf16 v[0:3], v[124:127], v[156:159], v[0:3]
	v_mfma_f32_16x16x32_bf16 v[0:3], v[128:131], v[160:163], v[0:3]
	v_mfma_f32_16x16x32_bf16 v[0:3], v[132:135], v[164:167], v[0:3]
	v_mfma_f32_16x16x32_bf16 v[0:3], v[136:139], v[168:171], v[0:3]
	v_mfma_f32_16x16x32_bf16 v[0:3], v[140:143], v[172:175], v[0:3]
	v_mfma_f32_16x16x32_bf16 v[0:3], v[144:147], v[176:179], v[0:3]
	v_mfma_f32_16x16x32_bf16 v[0:3], v[148:151], v[180:183], v[0:3]
	v_mfma_f32_16x16x32_bf16 v[0:3], v[152:155], v[184:187], v[0:3]
	s_waitcnt vmcnt(0)
	ds_read_b128 v[124:127], v100
	ds_read_b128 v[156:159], v108 offset:1536
	ds_read_b128 v[128:131], v101
	ds_read_b128 v[160:163], v109 offset:1536
	ds_read_b128 v[132:135], v102
	ds_read_b128 v[164:167], v110 offset:1536
	ds_read_b128 v[136:139], v103
	ds_read_b128 v[168:171], v111 offset:1536
	ds_read_b128 v[140:143], v104
	ds_read_b128 v[172:175], v112 offset:1536
	ds_read_b128 v[144:147], v105
	ds_read_b128 v[176:179], v113 offset:1536
	ds_read_b128 v[148:151], v106
	ds_read_b128 v[180:183], v114 offset:1536
	ds_read_b128 v[152:155], v107
	ds_read_b128 v[184:187], v115 offset:1536
	s_waitcnt lgkmcnt(0)
	v_mfma_f32_16x16x32_bf16 v[0:3], v[124:127], v[156:159], v[0:3]
	v_mfma_f32_16x16x32_bf16 v[0:3], v[128:131], v[160:163], v[0:3]
	v_mfma_f32_16x16x32_bf16 v[0:3], v[132:135], v[164:167], v[0:3]
	v_mfma_f32_16x16x32_bf16 v[0:3], v[136:139], v[168:171], v[0:3]
	v_mfma_f32_16x16x32_bf16 v[0:3], v[140:143], v[172:175], v[0:3]
	v_mfma_f32_16x16x32_bf16 v[0:3], v[144:147], v[176:179], v[0:3]
	v_mfma_f32_16x16x32_bf16 v[0:3], v[148:151], v[180:183], v[0:3]
	v_mfma_f32_16x16x32_bf16 v[0:3], v[152:155], v[184:187], v[0:3]
	s_and_b64 vcc, exec, s[2:3]
	s_cbranch_vccnz .LBB0_999
	s_nop 6
	ds_write_b128 v27, v[0:3]
